# sample-row out-projection tickets also offered (non-blocking, only when all sample units are done) before the prompt-FoX queue, so those 32 GEMM tiles no longer sit in the phase tail
# speedup vs baseline: 1.0070x; 1.0070x over previous
; #define LAS __attribute__((address_space(3)))
; __global__ void __launch_bounds__(NWAVES * 64, LBW) fwd_kernel(Args A) {
;     ...
;         {
;             volatile LAS unsigned* tslot = (volatile LAS unsigned*)(lds + AL_MISC) + 12;
;             __syncthreads();
;             if (tid == 0) { const unsigned tk = __hip_atomic_fetch_add(ctl + CW_OPQ, 1u, __ATOMIC_RELAXED, __HIP_MEMORY_SCOPE_AGENT);
;                 if (tk < 32u) { unsigned sp = 0; while (__hip_atomic_load(ctl + CW_SDONE, __ATOMIC_RELAXED, __HIP_MEMORY_SCOPE_AGENT) < 384u) { __builtin_amdgcn_s_sleep(8); if (++sp > (1u << 22)) break; }
;                     __builtin_amdgcn_fence(__ATOMIC_ACQUIRE, "agent"); asm volatile("s_waitcnt vmcnt(0)" ::: "memory"); }
;                 tslot[0] = tk; }
;             __syncthreads();
;             const unsigned tk = tslot[0];
.Ltk_first:
	s_mov_b32 s101, 1
	s_branch .LBB0_1057

; __global__ void __launch_bounds__(NWAVES * 64, LBW) fwd_kernel(Args A) {
;     ...
;             __syncthreads();
;             if (tid == 0) { const unsigned tk = __hip_atomic_fetch_add(ctl + CW_OPQ, 1u, __ATOMIC_RELAXED, __HIP_MEMORY_SCOPE_AGENT);
;                 if (tk < 32u) { unsigned sp = 0; while (__hip_atomic_load(ctl + CW_SDONE, __ATOMIC_RELAXED, __HIP_MEMORY_SCOPE_AGENT) < 384u) { __builtin_amdgcn_s_sleep(8); if (++sp > (1u << 22)) break; }
;                     __builtin_amdgcn_fence(__ATOMIC_ACQUIRE, "agent"); asm volatile("s_waitcnt vmcnt(0)" ::: "memory"); }
;                 tslot[0] = tk; }
.LBB0_1057:
	s_barrier
	s_mov_b64 s[2:3], exec
	v_readlane_b32 s0, v253, 26
	v_readlane_b32 s1, v253, 27
	s_and_b64 s[0:1], s[2:3], s[0:1]
	s_mov_b64 exec, s[0:1]
	s_cbranch_execz .LBB0_1071
	s_mov_b64 s[6:7], exec
	v_mbcnt_lo_u32_b32 v1, s6, 0
	v_mbcnt_hi_u32_b32 v1, s7, v1
	v_cmp_eq_u32_e32 vcc, 0, v1
	s_and_saveexec_b64 s[4:5], vcc
	s_cbranch_execz .LBB0_1060
	s_cmp_eq_u32 s101, 1
	s_cbranch_scc0 .Ltk_take
	v_readlane_b32 s98, v252, 6
	v_readlane_b32 s99, v252, 7
	v_mov_b32_e32 v2, 0
	s_nop 4
	global_load_dword v3, v2, s[98:99] sc1
	v_mov_b32_e32 v2, 0x1000
	s_waitcnt vmcnt(0)
	v_cmp_gt_u32_e32 vcc, 0x180, v3
	s_cbranch_vccnz .LBB0_1060
.Ltk_take:
	s_bcnt1_i32_b64 s0, s[6:7]
	v_mov_b32_e32 v2, 0x1000
	v_mov_b32_e32 v3, s0
	global_atomic_add v2, v2, v3, s[94:95] offset:256 sc0

; __global__ void __launch_bounds__(NWAVES * 64, LBW) fwd_kernel(Args A) {
;     ...
;             if (tk < 32u) {
;                 pg8::Gemm g{(const pg8::bf16_t*)(A.ws + WS_H), (const pg8::bf16_t*)(A.ws + WS_WTOUT), MT, D, D};
;                 pg8::OneUnit S1{64 + (int)(tk >> 2), (int)(tk & 3)};
;                 pg8::EpiOut E{(float*)(A.ws + WS_OUTF), (float*)(A.ws + WS_SS)};
;                 pg8::gemm_phase<pg8::EpiOut, pg8::OneUnit, false, true>(lds, g, S1, E);
;             }
;         }
.Ltk_exit:
	s_cmp_eq_u32 s101, 1
	s_cbranch_scc0 .LBB0_1095
	s_mov_b32 s101, 0
	s_branch .LBB0_801
